# out-proj residual epilogue: residual rows of the next three row blocks loaded ahead into three rotating 16-VGPR sets (counted waits), on top of v91
# baseline (speedup 1.0000x reference)
.LBB0_803:
	v_lshl_add_u32 v140, s91, 8, v3
	v_lshl_or_b32 v138, s90, 8, v143
	v_ashrrev_i32_e32 v141, 31, v140
	v_ashrrev_i32_e32 v139, 31, v138
	v_lshlrev_b64 v[146:147], 10, v[140:141]
	v_lshl_add_u64 v[154:155], v[146:147], 0, v[138:139]
	v_lshlrev_b64 v[156:157], 2, v[154:155]
	v_lshl_add_u64 v[158:159], s[28:29], 0, v[156:157]
	global_load_dwordx4 v[146:149], v[158:159], off
	global_load_dwordx4 v[150:153], v[158:159], off offset:16
	v_mov_b32_e32 v252, v158
	v_mov_b32_e32 v253, v159
	s_mov_b32 s98, 0x10000
	s_mov_b32 s99, 0
	v_lshl_add_u64 v[250:251], v[252:253], 0, s[98:99]
	global_load_dwordx4 v[180:183], v[250:251], off
	global_load_dwordx4 v[184:187], v[250:251], off offset:16
	global_load_dwordx4 v[188:191], v[250:251], off offset:512
	global_load_dwordx4 v[192:195], v[250:251], off offset:528
	s_mov_b32 s98, 0x20000
	s_mov_b32 s99, 0
	v_lshl_add_u64 v[250:251], v[252:253], 0, s[98:99]
	global_load_dwordx4 v[206:209], v[250:251], off
	global_load_dwordx4 v[210:213], v[250:251], off offset:16
	global_load_dwordx4 v[214:217], v[250:251], off offset:512
	global_load_dwordx4 v[218:221], v[250:251], off offset:528
	s_mov_b32 s98, 0x30000
	s_mov_b32 s99, 0
	v_lshl_add_u64 v[250:251], v[252:253], 0, s[98:99]
	global_load_dwordx4 v[164:167], v[250:251], off
	global_load_dwordx4 v[168:171], v[250:251], off offset:16
	global_load_dwordx4 v[172:175], v[250:251], off offset:512
	global_load_dwordx4 v[196:199], v[250:251], off offset:528
	v_lshl_add_u64 v[160:161], v[154:155], 1, s[50:51]
	v_lshl_add_u64 v[162:163], s[44:45], 0, v[156:157]
	v_xor_b32_e32 v145, 32, v204
	s_waitcnt vmcnt(12)
	v_pk_add_f32 v[130:131], v[130:131], v[148:149]
	v_pk_add_f32 v[128:129], v[128:129], v[146:147]
	v_pk_add_f32 v[148:149], v[126:127], v[152:153]
	v_pk_add_f32 v[146:147], v[124:125], v[150:151]
	global_store_dwordx4 v[162:163], v[128:131], off
	global_store_dwordx4 v[162:163], v[146:149], off offset:16
	v_cvt_pk_bf16_f32 v124, v128, v129
	v_cvt_pk_bf16_f32 v125, v130, v131
	v_cvt_pk_bf16_f32 v126, v146, v147
	v_cvt_pk_bf16_f32 v127, v148, v149
	global_store_dwordx4 v[160:161], v[124:127], off
	global_load_dwordx4 v[150:153], v[158:159], off offset:512
	global_load_dwordx4 v[154:157], v[158:159], off offset:528
	v_mul_f32_e32 v126, v129, v129
	v_mul_f32_e32 v127, v131, v131
	v_mul_f32_e32 v129, v147, v147
	v_mul_f32_e32 v131, v149, v149
	v_fmac_f32_e32 v126, v128, v128
	v_fmac_f32_e32 v127, v130, v130
	v_fmac_f32_e32 v129, v146, v146
	v_fmac_f32_e32 v131, v148, v148
	v_add_f32_e32 v126, v126, v127
	v_add_f32_e32 v127, v129, v131
	v_add_f32_e32 v130, v126, v127
	v_and_b32_e32 v125, 64, v204
	v_xor_b32_e32 v124, 16, v204
	v_add_u32_e32 v125, 64, v125
	v_cmp_lt_i32_e32 vcc, v124, v125
	s_waitcnt vmcnt(1)
	v_pk_add_f32 v[122:123], v[122:123], v[152:153]
	v_pk_add_f32 v[120:121], v[120:121], v[150:151]
	s_waitcnt vmcnt(0)
	v_pk_add_f32 v[128:129], v[118:119], v[156:157]
	v_pk_add_f32 v[126:127], v[116:117], v[154:155]
	v_mul_f32_e32 v116, v121, v121
	v_mul_f32_e32 v117, v123, v123
	v_mul_f32_e32 v118, v127, v127
	v_mul_f32_e32 v119, v129, v129
	v_fmac_f32_e32 v116, v120, v120
	v_fmac_f32_e32 v117, v122, v122
	v_fmac_f32_e32 v118, v126, v126
	v_fmac_f32_e32 v119, v128, v128
	v_add_f32_e32 v116, v116, v117
	v_add_f32_e32 v117, v118, v119
	v_cndmask_b32_e32 v124, v204, v124, vcc
	v_add_f32_e32 v116, v116, v117
	v_lshlrev_b32_e32 v124, 2, v124
	v_add_f32_e32 v116, v130, v116
	ds_bpermute_b32 v117, v124, v116
	v_cmp_lt_i32_e32 vcc, v145, v125
	global_store_dwordx4 v[162:163], v[120:123], off offset:512
	global_store_dwordx4 v[162:163], v[126:129], off offset:528
	v_cndmask_b32_e32 v118, v204, v145, vcc
	v_lshlrev_b32_e32 v118, 2, v118
	s_waitcnt lgkmcnt(0)
	v_add_f32_e32 v116, v116, v117
	ds_bpermute_b32 v117, v118, v116
	v_cvt_pk_bf16_f32 v120, v120, v121
	v_cvt_pk_bf16_f32 v121, v122, v123
	v_cvt_pk_bf16_f32 v122, v126, v127
	v_cvt_pk_bf16_f32 v123, v128, v129
	global_store_dwordx4 v[160:161], v[120:123], off offset:256
	s_and_saveexec_b64 s[24:25], s[40:41]
	s_cbranch_execz .LBB0_805
	v_lshl_add_u64 v[120:121], v[140:141], 2, s[46:47]
	s_waitcnt lgkmcnt(0)
	v_add_f32_e32 v116, v116, v117
	global_atomic_add_f32 v[120:121], v116, off
.LBB0_805:
	s_or_b64 exec, exec, s[24:25]
	v_or_b32_e32 v116, 16, v140
	s_waitcnt lgkmcnt(0)
	v_ashrrev_i32_e32 v117, 31, v116
	v_lshlrev_b64 v[120:121], 10, v[116:117]
	v_lshl_add_u64 v[130:131], v[120:121], 0, v[138:139]
	v_lshlrev_b64 v[146:147], 2, v[130:131]
	v_lshl_add_u64 v[148:149], s[28:29], 0, v[146:147]
	s_nop 0
	s_nop 0
	v_lshl_add_u64 v[130:131], v[130:131], 1, s[50:51]
	v_lshl_add_u64 v[146:147], s[44:45], 0, v[146:147]
	s_nop 0
	v_pk_add_f32 v[114:115], v[114:115], v[182:183]
	v_pk_add_f32 v[112:113], v[112:113], v[180:181]
	s_nop 0
	v_pk_add_f32 v[110:111], v[110:111], v[186:187]
	v_pk_add_f32 v[108:109], v[108:109], v[184:185]
	global_store_dwordx4 v[146:147], v[112:115], off
	global_store_dwordx4 v[146:147], v[108:111], off offset:16
	v_cvt_pk_bf16_f32 v120, v112, v113
	v_cvt_pk_bf16_f32 v121, v114, v115
	v_cvt_pk_bf16_f32 v122, v108, v109
	v_cvt_pk_bf16_f32 v123, v110, v111
	global_store_dwordx4 v[130:131], v[120:123], off
	s_nop 0
	s_nop 0
	s_nop 0
	v_mul_f32_e32 v113, v113, v113
	v_mul_f32_e32 v115, v115, v115
	v_mul_f32_e32 v109, v109, v109
	v_mul_f32_e32 v111, v111, v111
	v_fmac_f32_e32 v113, v112, v112
	v_fmac_f32_e32 v115, v114, v114
	v_fmac_f32_e32 v109, v108, v108
	v_fmac_f32_e32 v111, v110, v110
	v_add_f32_e32 v108, v113, v115
	v_add_f32_e32 v109, v109, v111
	v_add_f32_e32 v112, v108, v109
	s_nop 0
	v_pk_add_f32 v[106:107], v[106:107], v[190:191]
	v_pk_add_f32 v[104:105], v[104:105], v[188:189]
	s_nop 0
	v_pk_add_f32 v[110:111], v[102:103], v[194:195]
	v_pk_add_f32 v[108:109], v[100:101], v[192:193]
	s_mov_b32 s98, 0x80000
	s_mov_b32 s99, 0
	v_lshl_add_u64 v[250:251], v[252:253], 0, s[98:99]
	global_load_dwordx4 v[180:183], v[250:251], off
	global_load_dwordx4 v[184:187], v[250:251], off offset:16
	global_load_dwordx4 v[188:191], v[250:251], off offset:512
	global_load_dwordx4 v[192:195], v[250:251], off offset:528
	v_mul_f32_e32 v100, v105, v105
	v_mul_f32_e32 v101, v107, v107
	v_mul_f32_e32 v102, v109, v109
	v_mul_f32_e32 v103, v111, v111
	v_fmac_f32_e32 v100, v104, v104
	v_fmac_f32_e32 v101, v106, v106
	v_fmac_f32_e32 v102, v108, v108
	v_fmac_f32_e32 v103, v110, v110
	v_add_f32_e32 v100, v100, v101
	v_add_f32_e32 v101, v102, v103
	v_add_f32_e32 v100, v100, v101
	v_add_f32_e32 v100, v112, v100
	ds_bpermute_b32 v101, v124, v100
	global_store_dwordx4 v[146:147], v[104:107], off offset:512
	global_store_dwordx4 v[146:147], v[108:111], off offset:528
	v_cvt_pk_bf16_f32 v102, v104, v105
	v_cvt_pk_bf16_f32 v103, v106, v107
	s_waitcnt lgkmcnt(0)
	v_add_f32_e32 v100, v100, v101
	ds_bpermute_b32 v101, v118, v100
	v_cvt_pk_bf16_f32 v104, v108, v109
	v_cvt_pk_bf16_f32 v105, v110, v111
	global_store_dwordx4 v[130:131], v[102:105], off offset:256
	s_and_saveexec_b64 s[24:25], s[40:41]
	s_cbranch_execz .LBB0_807
	v_lshl_add_u64 v[102:103], v[116:117], 2, s[46:47]
	s_waitcnt lgkmcnt(0)
	v_add_f32_e32 v100, v100, v101
	global_atomic_add_f32 v[102:103], v100, off
.LBB0_807:
	s_or_b64 exec, exec, s[24:25]
	v_or_b32_e32 v100, 32, v140
	s_waitcnt lgkmcnt(0)
	v_ashrrev_i32_e32 v101, 31, v100
	v_lshlrev_b64 v[102:103], 10, v[100:101]
	v_lshl_add_u64 v[110:111], v[102:103], 0, v[138:139]
	v_lshlrev_b64 v[112:113], 2, v[110:111]
	v_lshl_add_u64 v[114:115], s[28:29], 0, v[112:113]
	s_nop 0
	s_nop 0
	v_lshl_add_u64 v[110:111], v[110:111], 1, s[50:51]
	v_lshl_add_u64 v[112:113], s[44:45], 0, v[112:113]
	s_nop 0
	v_pk_add_f32 v[98:99], v[98:99], v[208:209]
	v_pk_add_f32 v[96:97], v[96:97], v[206:207]
	s_nop 0
	v_pk_add_f32 v[94:95], v[94:95], v[212:213]
	v_pk_add_f32 v[92:93], v[92:93], v[210:211]
	global_store_dwordx4 v[112:113], v[96:99], off
	global_store_dwordx4 v[112:113], v[92:95], off offset:16
	v_cvt_pk_bf16_f32 v102, v96, v97
	v_cvt_pk_bf16_f32 v103, v98, v99
	v_cvt_pk_bf16_f32 v104, v92, v93
	v_cvt_pk_bf16_f32 v105, v94, v95
	global_store_dwordx4 v[110:111], v[102:105], off
	s_nop 0
	s_nop 0
	s_nop 0
	v_mul_f32_e32 v97, v97, v97
	v_mul_f32_e32 v99, v99, v99
	v_mul_f32_e32 v93, v93, v93
	v_mul_f32_e32 v95, v95, v95
	v_fmac_f32_e32 v97, v96, v96
	v_fmac_f32_e32 v99, v98, v98
	v_fmac_f32_e32 v93, v92, v92
	v_fmac_f32_e32 v95, v94, v94
	v_add_f32_e32 v92, v97, v99
	v_add_f32_e32 v93, v93, v95
	v_add_f32_e32 v96, v92, v93
	s_nop 0
	v_pk_add_f32 v[90:91], v[90:91], v[216:217]
	v_pk_add_f32 v[88:89], v[88:89], v[214:215]
	s_nop 0
	v_pk_add_f32 v[94:95], v[86:87], v[220:221]
	v_pk_add_f32 v[92:93], v[84:85], v[218:219]
	s_mov_b32 s98, 0x90000
	s_mov_b32 s99, 0
	v_lshl_add_u64 v[250:251], v[252:253], 0, s[98:99]
	global_load_dwordx4 v[206:209], v[250:251], off
	global_load_dwordx4 v[210:213], v[250:251], off offset:16
	global_load_dwordx4 v[214:217], v[250:251], off offset:512
	global_load_dwordx4 v[218:221], v[250:251], off offset:528
	v_mul_f32_e32 v84, v89, v89
	v_mul_f32_e32 v85, v91, v91
	v_mul_f32_e32 v86, v93, v93
	v_mul_f32_e32 v87, v95, v95
	v_fmac_f32_e32 v84, v88, v88
	v_fmac_f32_e32 v85, v90, v90
	v_fmac_f32_e32 v86, v92, v92
	v_fmac_f32_e32 v87, v94, v94
	v_add_f32_e32 v84, v84, v85
	v_add_f32_e32 v85, v86, v87
	v_add_f32_e32 v84, v84, v85
	v_add_f32_e32 v84, v96, v84
	ds_bpermute_b32 v85, v124, v84
	global_store_dwordx4 v[112:113], v[88:91], off offset:512
	global_store_dwordx4 v[112:113], v[92:95], off offset:528
	v_cvt_pk_bf16_f32 v86, v88, v89
	v_cvt_pk_bf16_f32 v87, v90, v91
	s_waitcnt lgkmcnt(0)
	v_add_f32_e32 v84, v84, v85
	ds_bpermute_b32 v85, v118, v84
	v_cvt_pk_bf16_f32 v88, v92, v93
	v_cvt_pk_bf16_f32 v89, v94, v95
	global_store_dwordx4 v[110:111], v[86:89], off offset:256
	s_and_saveexec_b64 s[24:25], s[40:41]
	s_cbranch_execz .LBB0_809
	v_lshl_add_u64 v[86:87], v[100:101], 2, s[46:47]
	s_waitcnt lgkmcnt(0)
	v_add_f32_e32 v84, v84, v85
	global_atomic_add_f32 v[86:87], v84, off
.LBB0_809:
	s_or_b64 exec, exec, s[24:25]
	v_or_b32_e32 v84, 48, v140
	s_waitcnt lgkmcnt(0)
	v_ashrrev_i32_e32 v85, 31, v84
	v_lshlrev_b64 v[86:87], 10, v[84:85]
	v_lshl_add_u64 v[94:95], v[86:87], 0, v[138:139]
	v_lshlrev_b64 v[96:97], 2, v[94:95]
	v_lshl_add_u64 v[98:99], s[28:29], 0, v[96:97]
	s_nop 0
	s_nop 0
	v_lshl_add_u64 v[94:95], v[94:95], 1, s[50:51]
	v_lshl_add_u64 v[96:97], s[44:45], 0, v[96:97]
	s_nop 0
	v_pk_add_f32 v[82:83], v[82:83], v[166:167]
	v_pk_add_f32 v[80:81], v[80:81], v[164:165]
	s_nop 0
	v_pk_add_f32 v[78:79], v[78:79], v[170:171]
	v_pk_add_f32 v[76:77], v[76:77], v[168:169]
	global_store_dwordx4 v[96:97], v[80:83], off
	global_store_dwordx4 v[96:97], v[76:79], off offset:16
	v_cvt_pk_bf16_f32 v86, v80, v81
	v_cvt_pk_bf16_f32 v87, v82, v83
	v_cvt_pk_bf16_f32 v88, v76, v77
	v_cvt_pk_bf16_f32 v89, v78, v79
	global_store_dwordx4 v[94:95], v[86:89], off
	s_nop 0
	s_nop 0
	s_nop 0
	v_mul_f32_e32 v81, v81, v81
	v_mul_f32_e32 v83, v83, v83
	v_mul_f32_e32 v77, v77, v77
	v_mul_f32_e32 v79, v79, v79
	v_fmac_f32_e32 v81, v80, v80
	v_fmac_f32_e32 v83, v82, v82
	v_fmac_f32_e32 v77, v76, v76
	v_fmac_f32_e32 v79, v78, v78
	v_add_f32_e32 v76, v81, v83
	v_add_f32_e32 v77, v77, v79
	v_add_f32_e32 v80, v76, v77
	s_nop 0
	v_pk_add_f32 v[74:75], v[74:75], v[174:175]
	v_pk_add_f32 v[72:73], v[72:73], v[172:173]
	s_nop 0
	v_pk_add_f32 v[78:79], v[70:71], v[198:199]
	v_pk_add_f32 v[76:77], v[68:69], v[196:197]
	s_mov_b32 s98, 0xa0000
	s_mov_b32 s99, 0
	v_lshl_add_u64 v[250:251], v[252:253], 0, s[98:99]
	global_load_dwordx4 v[164:167], v[250:251], off
	global_load_dwordx4 v[168:171], v[250:251], off offset:16
	global_load_dwordx4 v[172:175], v[250:251], off offset:512
	global_load_dwordx4 v[196:199], v[250:251], off offset:528
	v_mul_f32_e32 v68, v73, v73
	v_mul_f32_e32 v69, v75, v75
	v_mul_f32_e32 v70, v77, v77
	v_mul_f32_e32 v71, v79, v79
	v_fmac_f32_e32 v68, v72, v72
	v_fmac_f32_e32 v69, v74, v74
	v_fmac_f32_e32 v70, v76, v76
	v_fmac_f32_e32 v71, v78, v78
	v_add_f32_e32 v68, v68, v69
	v_add_f32_e32 v69, v70, v71
	v_add_f32_e32 v68, v68, v69
	v_add_f32_e32 v68, v80, v68
	ds_bpermute_b32 v69, v124, v68
	global_store_dwordx4 v[96:97], v[72:75], off offset:512
	global_store_dwordx4 v[96:97], v[76:79], off offset:528
	v_cvt_pk_bf16_f32 v70, v72, v73
	v_cvt_pk_bf16_f32 v71, v74, v75
	s_waitcnt lgkmcnt(0)
	v_add_f32_e32 v68, v68, v69
	ds_bpermute_b32 v69, v118, v68
	v_cvt_pk_bf16_f32 v72, v76, v77
	v_cvt_pk_bf16_f32 v73, v78, v79
	global_store_dwordx4 v[94:95], v[70:73], off offset:256
	s_and_saveexec_b64 s[24:25], s[40:41]
	s_cbranch_execz .LBB0_811
	v_lshl_add_u64 v[70:71], v[84:85], 2, s[46:47]
	s_waitcnt lgkmcnt(0)
	v_add_f32_e32 v68, v68, v69
	global_atomic_add_f32 v[70:71], v68, off
.LBB0_811:
	s_or_b64 exec, exec, s[24:25]
	v_add_u32_e32 v68, 0x80, v140
	s_waitcnt lgkmcnt(0)
	v_ashrrev_i32_e32 v69, 31, v68
	v_lshlrev_b64 v[70:71], 10, v[68:69]
	v_lshl_add_u64 v[78:79], v[70:71], 0, v[138:139]
	v_lshlrev_b64 v[80:81], 2, v[78:79]
	v_lshl_add_u64 v[82:83], s[28:29], 0, v[80:81]
	s_nop 0
	s_nop 0
	v_lshl_add_u64 v[78:79], v[78:79], 1, s[50:51]
	v_lshl_add_u64 v[80:81], s[44:45], 0, v[80:81]
	s_waitcnt vmcnt(26)
	v_pk_add_f32 v[66:67], v[66:67], v[182:183]
	v_pk_add_f32 v[64:65], v[64:65], v[180:181]
	s_waitcnt vmcnt(25)
	v_pk_add_f32 v[62:63], v[62:63], v[186:187]
	v_pk_add_f32 v[60:61], v[60:61], v[184:185]
	global_store_dwordx4 v[80:81], v[64:67], off
	global_store_dwordx4 v[80:81], v[60:63], off offset:16
	v_cvt_pk_bf16_f32 v70, v64, v65
	v_cvt_pk_bf16_f32 v71, v66, v67
	v_cvt_pk_bf16_f32 v72, v60, v61
	v_cvt_pk_bf16_f32 v73, v62, v63
	global_store_dwordx4 v[78:79], v[70:73], off
	s_nop 0
	s_nop 0
	s_nop 0
	v_mul_f32_e32 v65, v65, v65
	v_mul_f32_e32 v67, v67, v67
	v_mul_f32_e32 v61, v61, v61
	v_mul_f32_e32 v63, v63, v63
	v_fmac_f32_e32 v65, v64, v64
	v_fmac_f32_e32 v67, v66, v66
	v_fmac_f32_e32 v61, v60, v60
	v_fmac_f32_e32 v63, v62, v62
	v_add_f32_e32 v60, v65, v67
	v_add_f32_e32 v61, v61, v63
	v_add_f32_e32 v64, v60, v61
	s_waitcnt vmcnt(27)
	v_pk_add_f32 v[58:59], v[58:59], v[190:191]
	v_pk_add_f32 v[56:57], v[56:57], v[188:189]
	s_waitcnt vmcnt(26)
	v_pk_add_f32 v[62:63], v[54:55], v[194:195]
	v_pk_add_f32 v[60:61], v[52:53], v[192:193]
	s_mov_b32 s98, 0xb0000
	s_mov_b32 s99, 0
	v_lshl_add_u64 v[250:251], v[252:253], 0, s[98:99]
	global_load_dwordx4 v[180:183], v[250:251], off
	global_load_dwordx4 v[184:187], v[250:251], off offset:16
	global_load_dwordx4 v[188:191], v[250:251], off offset:512
	global_load_dwordx4 v[192:195], v[250:251], off offset:528
	v_mul_f32_e32 v52, v57, v57
	v_mul_f32_e32 v53, v59, v59
	v_mul_f32_e32 v54, v61, v61
	v_mul_f32_e32 v55, v63, v63
	v_fmac_f32_e32 v52, v56, v56
	v_fmac_f32_e32 v53, v58, v58
	v_fmac_f32_e32 v54, v60, v60
	v_fmac_f32_e32 v55, v62, v62
	v_add_f32_e32 v52, v52, v53
	v_add_f32_e32 v53, v54, v55
	v_add_f32_e32 v52, v52, v53
	v_add_f32_e32 v52, v64, v52
	ds_bpermute_b32 v53, v124, v52
	global_store_dwordx4 v[80:81], v[56:59], off offset:512
	global_store_dwordx4 v[80:81], v[60:63], off offset:528
	v_cvt_pk_bf16_f32 v54, v56, v57
	v_cvt_pk_bf16_f32 v55, v58, v59
	s_waitcnt lgkmcnt(0)
	v_add_f32_e32 v52, v52, v53
	ds_bpermute_b32 v53, v118, v52
	v_cvt_pk_bf16_f32 v56, v60, v61
	v_cvt_pk_bf16_f32 v57, v62, v63
	global_store_dwordx4 v[78:79], v[54:57], off offset:256
	s_and_saveexec_b64 s[24:25], s[40:41]
	s_cbranch_execz .LBB0_813
	v_lshl_add_u64 v[54:55], v[68:69], 2, s[46:47]
	s_waitcnt lgkmcnt(0)
	v_add_f32_e32 v52, v52, v53
	global_atomic_add_f32 v[54:55], v52, off
.LBB0_813:
	s_or_b64 exec, exec, s[24:25]
	v_add_u32_e32 v52, 0x90, v140
	s_waitcnt lgkmcnt(0)
	v_ashrrev_i32_e32 v53, 31, v52
	v_lshlrev_b64 v[54:55], 10, v[52:53]
	v_lshl_add_u64 v[62:63], v[54:55], 0, v[138:139]
	v_lshlrev_b64 v[64:65], 2, v[62:63]
	v_lshl_add_u64 v[66:67], s[28:29], 0, v[64:65]
	s_nop 0
	s_nop 0
	v_lshl_add_u64 v[62:63], v[62:63], 1, s[50:51]
	v_lshl_add_u64 v[64:65], s[44:45], 0, v[64:65]
	s_waitcnt vmcnt(26)
	v_pk_add_f32 v[50:51], v[50:51], v[208:209]
	v_pk_add_f32 v[48:49], v[48:49], v[206:207]
	s_waitcnt vmcnt(25)
	v_pk_add_f32 v[46:47], v[46:47], v[212:213]
	v_pk_add_f32 v[44:45], v[44:45], v[210:211]
	global_store_dwordx4 v[64:65], v[48:51], off
	global_store_dwordx4 v[64:65], v[44:47], off offset:16
	v_cvt_pk_bf16_f32 v54, v48, v49
	v_cvt_pk_bf16_f32 v55, v50, v51
	v_cvt_pk_bf16_f32 v56, v44, v45
	v_cvt_pk_bf16_f32 v57, v46, v47
	global_store_dwordx4 v[62:63], v[54:57], off
	s_nop 0
	s_nop 0
	s_nop 0
	v_mul_f32_e32 v49, v49, v49
	v_mul_f32_e32 v51, v51, v51
	v_mul_f32_e32 v45, v45, v45
	v_mul_f32_e32 v47, v47, v47
	v_fmac_f32_e32 v49, v48, v48
	v_fmac_f32_e32 v51, v50, v50
	v_fmac_f32_e32 v45, v44, v44
	v_fmac_f32_e32 v47, v46, v46
	v_add_f32_e32 v44, v49, v51
	v_add_f32_e32 v45, v45, v47
	v_add_f32_e32 v48, v44, v45
	s_waitcnt vmcnt(27)
	v_pk_add_f32 v[42:43], v[42:43], v[216:217]
	v_pk_add_f32 v[40:41], v[40:41], v[214:215]
	s_waitcnt vmcnt(26)
	v_pk_add_f32 v[46:47], v[38:39], v[220:221]
	v_pk_add_f32 v[44:45], v[36:37], v[218:219]
	v_mul_f32_e32 v36, v41, v41
	v_mul_f32_e32 v37, v43, v43
	v_mul_f32_e32 v38, v45, v45
	v_mul_f32_e32 v39, v47, v47
	v_fmac_f32_e32 v36, v40, v40
	v_fmac_f32_e32 v37, v42, v42
	v_fmac_f32_e32 v38, v44, v44
	v_fmac_f32_e32 v39, v46, v46
	v_add_f32_e32 v36, v36, v37
	v_add_f32_e32 v37, v38, v39
	v_add_f32_e32 v36, v36, v37
	v_add_f32_e32 v36, v48, v36
	ds_bpermute_b32 v37, v124, v36
	global_store_dwordx4 v[64:65], v[40:43], off offset:512
	global_store_dwordx4 v[64:65], v[44:47], off offset:528
	v_cvt_pk_bf16_f32 v38, v40, v41
	v_cvt_pk_bf16_f32 v39, v42, v43
	s_waitcnt lgkmcnt(0)
	v_add_f32_e32 v36, v36, v37
	ds_bpermute_b32 v37, v118, v36
	v_cvt_pk_bf16_f32 v40, v44, v45
	v_cvt_pk_bf16_f32 v41, v46, v47
	global_store_dwordx4 v[62:63], v[38:41], off offset:256
	s_and_saveexec_b64 s[24:25], s[40:41]
	s_cbranch_execz .LBB0_815
	v_lshl_add_u64 v[38:39], v[52:53], 2, s[46:47]
	s_waitcnt lgkmcnt(0)
	v_add_f32_e32 v36, v36, v37
	global_atomic_add_f32 v[38:39], v36, off
.LBB0_815:
	s_or_b64 exec, exec, s[24:25]
	v_add_u32_e32 v36, 0xa0, v140
	s_waitcnt lgkmcnt(0)
	v_ashrrev_i32_e32 v37, 31, v36
	v_lshlrev_b64 v[38:39], 10, v[36:37]
	v_lshl_add_u64 v[46:47], v[38:39], 0, v[138:139]
	v_lshlrev_b64 v[48:49], 2, v[46:47]
	v_lshl_add_u64 v[50:51], s[28:29], 0, v[48:49]
	s_nop 0
	s_nop 0
	v_lshl_add_u64 v[46:47], v[46:47], 1, s[50:51]
	v_lshl_add_u64 v[48:49], s[44:45], 0, v[48:49]
	s_waitcnt vmcnt(22)
	v_pk_add_f32 v[34:35], v[34:35], v[166:167]
	v_pk_add_f32 v[32:33], v[32:33], v[164:165]
	s_waitcnt vmcnt(21)
	v_pk_add_f32 v[30:31], v[30:31], v[170:171]
	v_pk_add_f32 v[28:29], v[28:29], v[168:169]
	global_store_dwordx4 v[48:49], v[32:35], off
	global_store_dwordx4 v[48:49], v[28:31], off offset:16
	v_cvt_pk_bf16_f32 v38, v32, v33
	v_cvt_pk_bf16_f32 v39, v34, v35
	v_cvt_pk_bf16_f32 v40, v28, v29
	v_cvt_pk_bf16_f32 v41, v30, v31
	global_store_dwordx4 v[46:47], v[38:41], off
	s_nop 0
	s_nop 0
	s_nop 0
	v_mul_f32_e32 v33, v33, v33
	v_mul_f32_e32 v35, v35, v35
	v_mul_f32_e32 v29, v29, v29
	v_mul_f32_e32 v31, v31, v31
	v_fmac_f32_e32 v33, v32, v32
	v_fmac_f32_e32 v35, v34, v34
	v_fmac_f32_e32 v29, v28, v28
	v_fmac_f32_e32 v31, v30, v30
	v_add_f32_e32 v28, v33, v35
	v_add_f32_e32 v29, v29, v31
	v_add_f32_e32 v32, v28, v29
	s_waitcnt vmcnt(23)
	v_pk_add_f32 v[26:27], v[26:27], v[174:175]
	v_pk_add_f32 v[24:25], v[24:25], v[172:173]
	s_waitcnt vmcnt(22)
	v_pk_add_f32 v[30:31], v[22:23], v[198:199]
	v_pk_add_f32 v[28:29], v[20:21], v[196:197]
	v_mul_f32_e32 v20, v25, v25
	v_mul_f32_e32 v21, v27, v27
	v_mul_f32_e32 v22, v29, v29
	v_mul_f32_e32 v23, v31, v31
	v_fmac_f32_e32 v20, v24, v24
	v_fmac_f32_e32 v21, v26, v26
	v_fmac_f32_e32 v22, v28, v28
	v_fmac_f32_e32 v23, v30, v30
	v_add_f32_e32 v20, v20, v21
	v_add_f32_e32 v21, v22, v23
	v_add_f32_e32 v20, v20, v21
	v_add_f32_e32 v20, v32, v20
	ds_bpermute_b32 v21, v124, v20
	global_store_dwordx4 v[48:49], v[24:27], off offset:512
	global_store_dwordx4 v[48:49], v[28:31], off offset:528
	v_cvt_pk_bf16_f32 v22, v24, v25
	v_cvt_pk_bf16_f32 v23, v26, v27
	s_waitcnt lgkmcnt(0)
	v_add_f32_e32 v20, v20, v21
	ds_bpermute_b32 v21, v118, v20
	v_cvt_pk_bf16_f32 v24, v28, v29
	v_cvt_pk_bf16_f32 v25, v30, v31
	global_store_dwordx4 v[46:47], v[22:25], off offset:256
	s_and_saveexec_b64 s[24:25], s[40:41]
	s_cbranch_execz .LBB0_817
	v_lshl_add_u64 v[22:23], v[36:37], 2, s[46:47]
	s_waitcnt lgkmcnt(0)
	v_add_f32_e32 v20, v20, v21
	global_atomic_add_f32 v[22:23], v20, off
.LBB0_817:
	s_or_b64 exec, exec, s[24:25]
	v_add_u32_e32 v20, 0xb0, v140
	s_waitcnt lgkmcnt(0)
	v_ashrrev_i32_e32 v21, 31, v20
	v_lshlrev_b64 v[22:23], 10, v[20:21]
	v_lshl_add_u64 v[30:31], v[22:23], 0, v[138:139]
	v_lshlrev_b64 v[32:33], 2, v[30:31]
	v_lshl_add_u64 v[34:35], s[28:29], 0, v[32:33]
	s_nop 0
	s_nop 0
	v_lshl_add_u64 v[30:31], v[30:31], 1, s[50:51]
	v_lshl_add_u64 v[32:33], s[44:45], 0, v[32:33]
	s_waitcnt vmcnt(18)
	v_pk_add_f32 v[18:19], v[18:19], v[182:183]
	v_pk_add_f32 v[16:17], v[16:17], v[180:181]
	s_waitcnt vmcnt(17)
	v_pk_add_f32 v[14:15], v[14:15], v[186:187]
	v_pk_add_f32 v[12:13], v[12:13], v[184:185]
	global_store_dwordx4 v[32:33], v[16:19], off
	global_store_dwordx4 v[32:33], v[12:15], off offset:16
	v_cvt_pk_bf16_f32 v22, v16, v17
	v_cvt_pk_bf16_f32 v23, v18, v19
	v_cvt_pk_bf16_f32 v24, v12, v13
	v_cvt_pk_bf16_f32 v25, v14, v15
	global_store_dwordx4 v[30:31], v[22:25], off
	s_nop 0
	s_nop 0
	s_nop 0
	v_mul_f32_e32 v17, v17, v17
	v_mul_f32_e32 v19, v19, v19
	v_mul_f32_e32 v13, v13, v13
	v_mul_f32_e32 v15, v15, v15
	v_fmac_f32_e32 v17, v16, v16
	v_fmac_f32_e32 v19, v18, v18
	v_fmac_f32_e32 v13, v12, v12
	v_fmac_f32_e32 v15, v14, v14
	v_add_f32_e32 v12, v17, v19
	v_add_f32_e32 v13, v13, v15
	v_add_f32_e32 v16, v12, v13
	s_waitcnt vmcnt(19)
	v_pk_add_f32 v[10:11], v[10:11], v[190:191]
	v_pk_add_f32 v[8:9], v[8:9], v[188:189]
	s_waitcnt vmcnt(18)
	v_pk_add_f32 v[14:15], v[6:7], v[194:195]
	v_pk_add_f32 v[12:13], v[4:5], v[192:193]
	v_mul_f32_e32 v4, v9, v9
	v_mul_f32_e32 v5, v11, v11
	v_mul_f32_e32 v6, v13, v13
	v_mul_f32_e32 v7, v15, v15
	v_fmac_f32_e32 v4, v8, v8
	v_fmac_f32_e32 v5, v10, v10
	v_fmac_f32_e32 v6, v12, v12
	v_fmac_f32_e32 v7, v14, v14
	v_add_f32_e32 v4, v4, v5
	v_add_f32_e32 v5, v6, v7
	v_add_f32_e32 v4, v4, v5
	v_add_f32_e32 v4, v16, v4
	ds_bpermute_b32 v5, v124, v4
	global_store_dwordx4 v[32:33], v[8:11], off offset:512
	global_store_dwordx4 v[32:33], v[12:15], off offset:528
	v_cvt_pk_bf16_f32 v6, v8, v9
	v_cvt_pk_bf16_f32 v7, v10, v11
	s_waitcnt lgkmcnt(0)
	v_add_f32_e32 v4, v4, v5
	ds_bpermute_b32 v5, v118, v4
	v_cvt_pk_bf16_f32 v8, v12, v13
	v_cvt_pk_bf16_f32 v9, v14, v15
	global_store_dwordx4 v[30:31], v[6:9], off offset:256
	s_and_saveexec_b64 s[24:25], s[40:41]
	s_cbranch_execz .LBB0_819
	v_lshl_add_u64 v[6:7], v[20:21], 2, s[46:47]
	s_waitcnt lgkmcnt(0)
	v_add_f32_e32 v4, v4, v5
	global_atomic_add_f32 v[6:7], v4, off
